# attention unit end: drain only the DMA pieces (vmcnt(4)), the O stores stay in flight under the next unit's Q loads
# speedup vs baseline: 1.0109x; 1.0017x over previous
; __device__ __forceinline__ unsigned f2bf(float f) { unsigned u = __builtin_bit_cast(unsigned, f); return (u + 0x7fffu + ((u >> 16) & 1u)) >> 16; }
; __device__ __forceinline__ int crow(int r, int hi) { return (r & 3) + 8 * (r >> 2) + 4 * hi; }
; __device__ __forceinline__ void attn_body(const bf16* __restrict__ Qb, const bf16* __restrict__ Kh, const bf16* __restrict__ Vh, bf16* __restrict__ Ob, int seq, float m0l2, char* lds, bool pre, bool post) {
;     ...
;     { auto rr = __builtin_amdgcn_permlane32_swap(__float_as_uint(l_reg), __float_as_uint(l_reg), false, false); l_reg = __uint_as_float(rr[0]) + __uint_as_float(rr[1]); }
;     if (hi == 0) li_l[r32] = l_reg; asm volatile("s_waitcnt lgkmcnt(0)" ::: "memory");
;     float rli[16];
; #pragma unroll
;     for (int r = 0; r < 16; ++r) rli[r] = __builtin_amdgcn_rcpf(li_l[crow(r, hi)]);
;     bf16* Ow = Ob + (long)(wid * QBLK) * LDO;
;     {
;         bf16* stg = (bf16*)(lds + OFF_OST) + wid * 2048;
; #pragma unroll
;         for (int r = 0; r < 16; ++r) { const int orow = crow(r, hi);
; #pragma unroll
;             for (int d0 = 0; d0 < 2; ++d0) stg[orow * 64 + d0 * 32 + r32] = (bf16)f2bf(o[d0][r] * rli[r]); }
;         asm volatile("s_waitcnt lgkmcnt(0)" ::: "memory");
; #pragma unroll
;         for (int i = 0; i < 4; ++i) { const int row = i * 8 + (lane >> 3), ch = lane & 7; const u32x4 v = *(const u32x4*)(stg + row * 64 + ch * 8); *(u32x4*)(Ow + (long)row * LDO + ch * 8) = v; }
;     }
;     asm volatile("s_waitcnt vmcnt(0)" ::: "memory");
;     __syncthreads();
.LBB0_23:
	s_or_b64 exec, exec, s[6:7]
	s_waitcnt lgkmcnt(0)
	v_add_u32_e32 v56, v96, v130
	ds_read_b128 v[48:51], v56
	ds_read_b128 v[52:55], v56 offset:32
	s_lshl_b64 s[6:7], s[10:11], 11
	s_add_u32 s6, s16, s6
	s_addc_u32 s7, s17, s7
	s_waitcnt lgkmcnt(0)
	v_rcp_f32_e32 v57, v48
	s_lshl_b32 s10, s25, 1
	s_add_u32 s6, s6, s10
	v_readlane_b32 s10, v255, 1
	v_lshlrev_b32_e32 v67, 9, v152
	v_lshlrev_b32_e32 v68, 1, v150
	v_lshl_add_u32 v66, v151, 12, s10
	v_mul_f32_e32 v32, v32, v57
	v_rcp_f32_e32 v58, v49
	v_add3_u32 v67, v66, v67, v68
	v_bfe_u32 v68, v32, 16, 1
	v_add3_u32 v32, v32, v68, s56
	v_mul_f32_e32 v16, v16, v57
	ds_write_b16_d16_hi v67, v32
	v_bfe_u32 v32, v16, 16, 1
	v_add3_u32 v16, v16, v32, s56
	ds_write_b16_d16_hi v67, v16 offset:64
	v_mul_f32_e32 v16, v33, v58
	v_bfe_u32 v32, v16, 16, 1
	v_rcp_f32_e32 v59, v50
	v_add3_u32 v16, v16, v32, s56
	ds_write_b16_d16_hi v67, v16 offset:128
	v_mul_f32_e32 v16, v17, v58
	v_bfe_u32 v17, v16, 16, 1
	v_add3_u32 v16, v16, v17, s56
	ds_write_b16_d16_hi v67, v16 offset:192
	v_mul_f32_e32 v16, v34, v59
	v_bfe_u32 v17, v16, 16, 1
	v_rcp_f32_e32 v60, v51
	v_add3_u32 v16, v16, v17, s56
	ds_write_b16_d16_hi v67, v16 offset:256
	v_mul_f32_e32 v16, v18, v59
	v_bfe_u32 v17, v16, 16, 1
	v_add3_u32 v16, v16, v17, s56
	ds_write_b16_d16_hi v67, v16 offset:320
	v_mul_f32_e32 v16, v35, v60
	v_bfe_u32 v17, v16, 16, 1
	v_rcp_f32_e32 v61, v52
	v_add3_u32 v16, v16, v17, s56
	ds_write_b16_d16_hi v67, v16 offset:384
	v_mul_f32_e32 v16, v19, v60
	v_bfe_u32 v17, v16, 16, 1
	v_add3_u32 v16, v16, v17, s56
	ds_write_b16_d16_hi v67, v16 offset:448
	v_mul_f32_e32 v16, v36, v61
	v_bfe_u32 v17, v16, 16, 1
	v_rcp_f32_e32 v62, v53
	v_add3_u32 v16, v16, v17, s56
	ds_write_b16_d16_hi v67, v16 offset:1024
	v_mul_f32_e32 v16, v20, v61
	v_bfe_u32 v17, v16, 16, 1
	v_add3_u32 v16, v16, v17, s56
	ds_write_b16_d16_hi v67, v16 offset:1088
	v_mul_f32_e32 v16, v37, v62
	v_bfe_u32 v17, v16, 16, 1
	v_rcp_f32_e32 v63, v54
	v_add3_u32 v16, v16, v17, s56
	ds_write_b16_d16_hi v67, v16 offset:1152
	v_mul_f32_e32 v16, v21, v62
	v_bfe_u32 v17, v16, 16, 1
	v_add3_u32 v16, v16, v17, s56
	ds_write_b16_d16_hi v67, v16 offset:1216
	v_mul_f32_e32 v16, v38, v63
	v_bfe_u32 v17, v16, 16, 1
	v_rcp_f32_e32 v64, v55
	v_add3_u32 v16, v16, v17, s56
	ds_read_b128 v[48:51], v56 offset:64
	ds_read_b128 v[52:55], v56 offset:96
	ds_write_b16_d16_hi v67, v16 offset:1280
	v_mul_f32_e32 v16, v22, v63
	v_bfe_u32 v17, v16, 16, 1
	v_add3_u32 v16, v16, v17, s56
	ds_write_b16_d16_hi v67, v16 offset:1344
	v_mul_f32_e32 v16, v39, v64
	v_bfe_u32 v17, v16, 16, 1
	s_waitcnt lgkmcnt(0)
	v_rcp_f32_e32 v56, v48
	v_add3_u32 v16, v16, v17, s56
	ds_write_b16_d16_hi v67, v16 offset:1408
	v_mul_f32_e32 v16, v23, v64
	v_bfe_u32 v17, v16, 16, 1
	v_add3_u32 v16, v16, v17, s56
	ds_write_b16_d16_hi v67, v16 offset:1472
	v_mul_f32_e32 v16, v40, v56
	v_bfe_u32 v17, v16, 16, 1
	v_rcp_f32_e32 v65, v49
	v_add3_u32 v16, v16, v17, s56
	ds_write_b16_d16_hi v67, v16 offset:2048
	v_mul_f32_e32 v16, v24, v56
	v_bfe_u32 v17, v16, 16, 1
	v_add3_u32 v16, v16, v17, s56
	ds_write_b16_d16_hi v67, v16 offset:2112
	v_mul_f32_e32 v16, v41, v65
	v_bfe_u32 v17, v16, 16, 1
	v_rcp_f32_e32 v50, v50
	v_add3_u32 v16, v16, v17, s56
	ds_write_b16_d16_hi v67, v16 offset:2176
	v_mul_f32_e32 v16, v25, v65
	v_bfe_u32 v17, v16, 16, 1
	v_add3_u32 v16, v16, v17, s56
	ds_write_b16_d16_hi v67, v16 offset:2240
	v_mul_f32_e32 v16, v42, v50
	v_bfe_u32 v17, v16, 16, 1
	v_rcp_f32_e32 v51, v51
	v_add3_u32 v16, v16, v17, s56
	ds_write_b16_d16_hi v67, v16 offset:2304
	v_mul_f32_e32 v16, v26, v50
	v_bfe_u32 v17, v16, 16, 1
	v_add3_u32 v16, v16, v17, s56
	ds_write_b16_d16_hi v67, v16 offset:2368
	v_mul_f32_e32 v16, v43, v51
	v_bfe_u32 v17, v16, 16, 1
	v_rcp_f32_e32 v52, v52
	v_add3_u32 v16, v16, v17, s56
	ds_write_b16_d16_hi v67, v16 offset:2432
	v_mul_f32_e32 v16, v27, v51
	v_bfe_u32 v17, v16, 16, 1
	v_add3_u32 v16, v16, v17, s56
	ds_write_b16_d16_hi v67, v16 offset:2496
	v_mul_f32_e32 v16, v44, v52
	v_bfe_u32 v17, v16, 16, 1
	v_rcp_f32_e32 v53, v53
	v_add3_u32 v16, v16, v17, s56
	ds_write_b16_d16_hi v67, v16 offset:3072
	v_mul_f32_e32 v16, v28, v52
	v_bfe_u32 v17, v16, 16, 1
	v_add3_u32 v16, v16, v17, s56
	ds_write_b16_d16_hi v67, v16 offset:3136
	v_mul_f32_e32 v16, v45, v53
	v_bfe_u32 v17, v16, 16, 1
	v_rcp_f32_e32 v54, v54
	v_add3_u32 v16, v16, v17, s56
	ds_write_b16_d16_hi v67, v16 offset:3200
	v_mul_f32_e32 v16, v29, v53
	v_bfe_u32 v17, v16, 16, 1
	v_add3_u32 v16, v16, v17, s56
	ds_write_b16_d16_hi v67, v16 offset:3264
	v_mul_f32_e32 v16, v46, v54
	v_bfe_u32 v17, v16, 16, 1
	v_rcp_f32_e32 v55, v55
	v_add3_u32 v16, v16, v17, s56
	ds_write_b16_d16_hi v67, v16 offset:3328
	v_mul_f32_e32 v16, v30, v54
	v_bfe_u32 v17, v16, 16, 1
	v_add3_u32 v16, v16, v17, s56
	ds_write_b16_d16_hi v67, v16 offset:3392
	v_mul_f32_e32 v16, v47, v55
	v_bfe_u32 v17, v16, 16, 1
	v_add3_u32 v16, v16, v17, s56
	ds_write_b16_d16_hi v67, v16 offset:3456
	v_mul_f32_e32 v16, v31, v55
	v_ashrrev_i32_e32 v129, 31, v128
	v_bfe_u32 v17, v16, 16, 1
	v_lshlrev_b32_e32 v18, 4, v149
	s_addc_u32 s7, s7, 0
	v_lshlrev_b64 v[48:49], 11, v[128:129]
	v_add3_u32 v16, v16, v17, s56
	v_and_b32_e32 v160, 0x70, v18
	ds_write_b16_d16_hi v67, v16 offset:3520
	v_lshl_add_u64 v[16:17], s[6:7], 0, v[48:49]
	v_lshrrev_b32_e32 v28, 3, v131
	v_add_u32_e32 v29, v66, v160
	s_waitcnt lgkmcnt(0)
	v_lshl_add_u64 v[24:25], v[16:17], 0, v[160:161]
	v_lshl_add_u32 v16, v28, 7, v29
	v_or_b32_e32 v30, 8, v28
	ds_read_b128 v[16:19], v16
	v_lshl_add_u32 v20, v30, 7, v29
	ds_read_b128 v[20:23], v20
	v_lshlrev_b32_e32 v160, 11, v28
	v_lshl_add_u64 v[26:27], v[24:25], 0, v[160:161]
	v_lshlrev_b32_e32 v160, 11, v30
	s_waitcnt lgkmcnt(0)
	global_store_dwordx4 v[26:27], v[16:19], off
	s_add_i32 s23, s23, 1
	s_mul_i32 s6, s23, s24
	v_lshl_add_u64 v[16:17], v[24:25], 0, v[160:161]
	global_store_dwordx4 v[16:17], v[20:23], off
	s_add_i32 s6, s6, s2
	s_cmpk_lt_i32 s6, 0x400
	v_or_b32_e32 v20, 16, v28
	v_lshl_add_u32 v16, v20, 7, v29
	v_or_b32_e32 v28, 24, v28
	ds_read_b128 v[16:19], v16
	v_lshlrev_b32_e32 v160, 11, v20
	v_lshl_add_u32 v20, v28, 7, v29
	ds_read_b128 v[20:23], v20
	v_lshl_add_u64 v[26:27], v[24:25], 0, v[160:161]
	v_lshlrev_b32_e32 v160, 11, v28
	s_waitcnt lgkmcnt(0)
	global_store_dwordx4 v[26:27], v[16:19], off
	s_nop 1
	v_lshl_add_u64 v[16:17], v[24:25], 0, v[160:161]
	global_store_dwordx4 v[16:17], v[20:23], off
	s_waitcnt vmcnt(4)
	s_waitcnt vmcnt(4)
	s_barrier
	s_cbranch_scc0 .LBB0_32
